# baseline (speedup 1.0000x reference)
; DI float bf2f(short b) { return __uint_as_float(((unsigned)(unsigned short)b) << 16); }
; DI bf16x8 pack8(const float* a) { u32x4 w = {cvtpk(a[0], a[1]), cvtpk(a[2], a[3]), cvtpk(a[4], a[5]), cvtpk(a[6], a[7])}; return *reinterpret_cast<bf16x8*>(&w); }
; DI int bid_() { int b = blockIdx.x; asm volatile("" : "+s"(b)); return b; }
; DI void attn_item_dma(const u16* Qb, const u16* Kh, const u16* Vh, const u16* Rh, u16* Ob, int seq, const float* rope, int pos0, char* lds) {
;     ...
;   const u16* Qw = Qb + (size_t)(wid * 32 + r32) * LDQ + hi * 8;
; #pragma unroll
;   for (int d0 = 0; d0 < 8; ++d0) qr[d0] = ld8(Qw + d0 * 16);
;   { const float* rp = rope + (size_t)(pos0 + wid * 32 + r32) * 64 + hi * 8;
; #pragma unroll
;     for (int f = 0; f < 2; ++f) {
;       const bf16x8 x1 = ld8(Qw + (8 + f) * 16), x2 = ld8(Qw + (10 + f) * 16);
;       const float4 c0 = *reinterpret_cast<const float4*>(rp + f * 16), c1 = *reinterpret_cast<const float4*>(rp + f * 16 + 4);
;       const float4 s0 = *reinterpret_cast<const float4*>(rp + 32 + f * 16), s1 = *reinterpret_cast<const float4*>(rp + 32 + f * 16 + 4);
;       const float cc[8] = {c0.x, c0.y, c0.z, c0.w, c1.x, c1.y, c1.z, c1.w}, ss[8] = {s0.x, s0.y, s0.z, s0.w, s1.x, s1.y, s1.z, s1.w};
;       float o1[8], o2[8];
; #pragma unroll
;       for (int j = 0; j < 8; ++j) { const float a = bf2f(x1[j]), b = bf2f(x2[j]); o1[j] = a * cc[j] - b * ss[j]; o2[j] = a * ss[j] + b * cc[j]; }
;       qr[8 + f] = pack8(o1); qr[10 + f] = pack8(o2);
;     } }
; DI void phase_attn(const u16* Q, const u16* KV, const u16* KR, u16* OM, int L, const float* rope, char* lds) {
;     ...
;   for (int it = bid_(); it < 512; it += gridDim.x) {
;     const int h = it & 7, rest = it >> 3;
;     const int seq = rest / nqb, qb = rest % nqb;
;     const size_t tok0 = (size_t)seq * L;
.LBB0_121:
	s_and_b32 s2, s50, 7
	s_lshl_b32 s6, s2, 9
	s_ashr_i32 s2, s59, 3
	s_abs_i32 s12, s2
	s_mul_hi_u32 s13, s12, s58
	s_mul_i32 s36, s13, s54
	s_ashr_i32 s7, s59, 31
	s_sub_i32 s12, s12, s36
	s_and_b32 s60, s59, 7
	s_xor_b32 s7, s7, s55
	s_add_i32 s36, s13, 1
	s_sub_i32 s37, s12, s54
	s_cmp_ge_u32 s12, s54
	s_cselect_b32 s13, s36, s13
	s_cselect_b32 s12, s37, s12
	s_add_i32 s36, s13, 1
	s_cmp_ge_u32 s12, s54
	s_cselect_b32 s12, s36, s13
	s_xor_b32 s12, s12, s7
	s_sub_i32 s12, s12, s7
	s_mul_i32 s7, s12, s51
	s_sub_i32 s2, s2, s7
	s_waitcnt vmcnt(0)
	v_mov_b32_e32 v58, v232
	s_lshl_b32 s2, s2, 8
	s_ashr_i32 s13, s12, 31
	v_and_b32_e32 v170, 31, v58
	v_ashrrev_i32_e32 v10, 1, v58
	v_and_b32_e32 v146, 0xffffffe0, v10
	v_or_b32_e32 v0, s2, v170
	v_add_u32_e32 v0, v0, v146
	v_ashrrev_i32_e32 v1, 31, v0
	s_lshl_b64 s[36:37], s[12:13], s53
	s_ashr_i32 s7, s2, 31
	v_lshlrev_b64 v[0:1], 8, v[0:1]
	s_add_u32 s40, s36, s2
	v_lshl_add_u64 v[0:1], s[48:49], 0, v[0:1]
	v_and_b32_e32 v2, 32, v58
	v_mov_b32_e32 v3, v97
	s_addc_u32 s41, s37, s7
	v_lshl_add_u64 v[0:1], v[0:1], 0, v[2:3]
	s_mul_i32 s7, s41, 0xc00
	s_mul_hi_u32 s12, s40, 0xc00
	global_load_dwordx4 v[2:5], v[0:1], off offset:128
	global_load_dwordx4 v[6:9], v[0:1], off
	s_add_i32 s12, s12, s7
	s_mul_i32 s7, s40, 0xc00
	s_add_u32 s7, s46, s7
	s_addc_u32 s13, s47, s12
	s_mul_i32 s2, s60, 0x180
	s_add_u32 s12, s7, s2
	s_addc_u32 s13, s13, 0
	s_movk_i32 s2, 0xffe0
	v_bfe_u32 v171, v58, 5, 1
	v_bfi_b32 v12, s2, v10, v58
	v_mov_b64_e32 v[10:11], s[12:13]
	s_movk_i32 s2, 0xc00
	v_mad_i64_i32 v[10:11], s[12:13], v12, s2, v[10:11]
	v_lshlrev_b32_e32 v96, 4, v171
	v_lshl_add_u64 v[26:27], v[10:11], 0, v[96:97]
	global_load_dwordx4 v[10:13], v[0:1], off offset:144
	global_load_dwordx4 v[14:17], v[0:1], off offset:16
	global_load_dwordx4 v[18:21], v[26:27], off offset:256
	global_load_dwordx4 v[22:25], v[26:27], off offset:320
	global_load_dwordx4 v[134:137], v[26:27], off
	global_load_dwordx4 v[130:133], v[26:27], off offset:32
	global_load_dwordx4 v[126:129], v[26:27], off offset:64
	global_load_dwordx4 v[114:117], v[26:27], off offset:96
	global_load_dwordx4 v[110:113], v[26:27], off offset:128
	global_load_dwordx4 v[106:109], v[26:27], off offset:160
	global_load_dwordx4 v[102:105], v[26:27], off offset:192
	global_load_dwordx4 v[98:101], v[26:27], off offset:224
	s_lshl_b64 s[38:39], s[36:37], 12
	s_add_u32 s2, s14, s38
	v_lshlrev_b32_e32 v82, 3, v58
	s_addc_u32 s7, s15, s39
	s_lshl_b32 s12, s60, 9
	v_lshlrev_b32_e32 v175, 4, v58
	v_bfe_u32 v59, v58, 2, 2
	s_add_u32 s44, s2, s12
	s_movk_i32 s2, 0x70
	s_addc_u32 s45, s7, 0
	v_add_u32_e32 v178, 16, v175
	s_mov_b64 s[12:13], 0x20100
	v_mov_b32_e32 v49, v97
	s_lshl_b64 s[42:43], s[36:37], 7
	s_add_u32 s36, s56, s42
	s_addc_u32 s37, s57, s43
	v_mov_b32_e32 v51, v97
	v_lshlrev_b32_e32 v74, 8, v170
	v_and_b32_e32 v75, 0x70, v175
	v_bitop3_b32 v176, v96, v74, v75 bitop3:0xde
	v_or_b32_e32 v83, 32, v96
	v_bitop3_b32 v179, v83, v74, v75 bitop3:0xde
	v_add_u32_e32 v76, 16, v179
	v_or_b32_e32 v84, 64, v96
	v_bitop3_b32 v180, v84, v74, v75 bitop3:0xde
	v_add_u32_e32 v85, 16, v180
	v_or_b32_e32 v86, 0x60, v96
	v_bitop3_b32 v181, v86, v74, v75 bitop3:0xde
	v_add_u32_e32 v87, 16, v181
	s_mov_b32 s84, s85
	s_mov_b32 s86, s85
	s_mov_b32 s87, s85
	s_mov_b32 s88, s85
	s_mov_b32 s89, s85
	s_mov_b32 s90, s85
	s_mov_b32 s91, s85
	s_mov_b32 s92, s85
	s_mov_b32 s93, s85
	s_mov_b32 s94, s85
	s_mov_b32 s95, s85
	s_mov_b32 s96, s85
	s_mov_b32 s97, s85
	s_mov_b32 s98, s85
	s_mov_b32 s99, s85
	s_mov_b32 s61, 1
	v_mov_b32_e32 v173, 0
	s_waitcnt vmcnt(13)
	v_mov_b32_e32 v28, v2
	s_waitcnt vmcnt(12)
	v_mov_b32_e32 v29, v6
	v_mov_b32_e32 v30, v6
	v_mov_b32_e32 v31, v2
	v_mov_b32_e32 v6, v3
	v_mov_b32_e32 v2, v7
	v_mov_b32_e32 v32, v4
	s_waitcnt vmcnt(11)
	v_mov_b32_e32 v36, v10
	s_waitcnt vmcnt(10)
	v_mov_b32_e32 v37, v14
	s_waitcnt vmcnt(9)
	v_and_b32_e32 v41, 0xffff0000, v18
	s_waitcnt vmcnt(8)
	v_and_b32_e32 v40, 0xffff0000, v22
	v_lshlrev_b32_e32 v39, 16, v18
	v_lshlrev_b32_e32 v38, 16, v22
	v_lshlrev_b32_e32 v42, 16, v23
	v_and_b32_e32 v18, 0xffff0000, v23
	v_lshlrev_b32_e32 v23, 16, v20
	v_lshlrev_b32_e32 v22, 16, v24
	v_pk_mul_f32 v[6:7], v[6:7], v[40:41]
	v_pk_mul_f32 v[2:3], v[2:3], v[40:41]
	v_mov_b32_e32 v33, v8
	v_mov_b32_e32 v34, v8
	v_mov_b32_e32 v35, v4
	v_mov_b32_e32 v8, v5
	v_mov_b32_e32 v4, v9
	v_lshlrev_b32_e32 v43, 16, v19
	v_and_b32_e32 v19, 0xffff0000, v19
	v_pk_mul_f32 v[30:31], v[30:31], v[38:39]
	v_sub_f32_e32 v6, v7, v6
	v_add_f32_e32 v7, v2, v3
	v_pk_mul_f32 v[2:3], v[36:37], v[22:23]
	v_pk_mul_f32 v[8:9], v[8:9], v[18:19]
	v_pk_mul_f32 v[4:5], v[4:5], v[18:19]
	v_add_f32_e32 v19, v30, v31
	v_sub_f32_e32 v30, v3, v2
	v_mov_b32_e32 v2, v14
	v_mov_b32_e32 v3, v10
	v_pk_mul_f32 v[2:3], v[2:3], v[22:23]
	v_mov_b32_e32 v14, v11
	v_add_f32_e32 v22, v2, v3
	v_and_b32_e32 v3, 0xffff0000, v20
	v_and_b32_e32 v2, 0xffff0000, v24
	v_mov_b32_e32 v10, v15
	v_sub_f32_e32 v8, v9, v8
	v_add_f32_e32 v9, v4, v5
	v_pk_mul_f32 v[4:5], v[14:15], v[2:3]
	v_pk_mul_f32 v[2:3], v[10:11], v[2:3]
	v_sub_f32_e32 v14, v5, v4
	v_add_f32_e32 v10, v2, v3
	v_lshlrev_b32_e32 v3, 16, v21
	v_lshlrev_b32_e32 v2, 16, v25
	v_mov_b32_e32 v4, v12
	v_mov_b32_e32 v5, v16
	v_pk_mul_f32 v[4:5], v[4:5], v[2:3]
	v_pk_mul_f32 v[28:29], v[28:29], v[38:39]
	v_sub_f32_e32 v11, v5, v4
	v_mov_b32_e32 v4, v16
	v_mov_b32_e32 v5, v12
	v_pk_mul_f32 v[2:3], v[4:5], v[2:3]
	v_mov_b32_e32 v16, v13
	v_add_f32_e32 v15, v2, v3
	v_and_b32_e32 v3, 0xffff0000, v21
	v_and_b32_e32 v2, 0xffff0000, v25
	v_mov_b32_e32 v12, v17
	v_pk_mul_f32 v[4:5], v[16:17], v[2:3]
	v_pk_mul_f32 v[2:3], v[12:13], v[2:3]
	v_pk_mul_f32 v[32:33], v[32:33], v[42:43]
	v_pk_mul_f32 v[34:35], v[34:35], v[42:43]
	v_sub_f32_e32 v18, v29, v28
	v_sub_f32_e32 v4, v5, v4
	v_add_f32_e32 v2, v2, v3
	v_sub_f32_e32 v28, v33, v32
	v_add_f32_e32 v29, v34, v35
	v_cvt_pk_bf16_f32 v122, v18, v6
	v_cvt_pk_bf16_f32 v123, v28, v8
	v_cvt_pk_bf16_f32 v124, v30, v14
	v_cvt_pk_bf16_f32 v125, v11, v4
	v_cvt_pk_bf16_f32 v118, v19, v7
	v_cvt_pk_bf16_f32 v119, v29, v9
	v_cvt_pk_bf16_f32 v120, v22, v10
	v_cvt_pk_bf16_f32 v121, v15, v2
	global_load_dwordx4 v[2:5], v[26:27], off offset:288
	global_load_dwordx4 v[6:9], v[26:27], off offset:352
	global_load_dwordx4 v[10:13], v[0:1], off offset:192
	global_load_dwordx4 v[14:17], v[0:1], off offset:64
	global_load_dwordx4 v[18:21], v[0:1], off offset:208
	global_load_dwordx4 v[22:25], v[0:1], off offset:80
	s_waitcnt vmcnt(5)
; DI float bf2f(short b) { return __uint_as_float(((unsigned)(unsigned short)b) << 16); }
; DI bf16x8 pack8(const float* a) { u32x4 w = {cvtpk(a[0], a[1]), cvtpk(a[2], a[3]), cvtpk(a[4], a[5]), cvtpk(a[6], a[7])}; return *reinterpret_cast<bf16x8*>(&w); }
; DI int v_rd_base(int lane) { return ((lane & 3) << 3) | (((lane >> 2) & 3) << 6) | (((lane >> 4) & 1) << 5) | (((lane >> 5) & 1) << 8); }
; #define VWAIT() asm volatile("s_waitcnt vmcnt(0)" ::: "memory")
; DI void attn_item_dma(const u16* Qb, const u16* Kh, const u16* Vh, const u16* Rh, u16* Ob, int seq, const float* rope, int pos0, char* lds) {
;     ...
;       const bf16x8 x1 = ld8(Qw + (8 + f) * 16), x2 = ld8(Qw + (10 + f) * 16);
;       const float4 c0 = *reinterpret_cast<const float4*>(rp + f * 16), c1 = *reinterpret_cast<const float4*>(rp + f * 16 + 4);
;       const float4 s0 = *reinterpret_cast<const float4*>(rp + 32 + f * 16), s1 = *reinterpret_cast<const float4*>(rp + 32 + f * 16 + 4);
;       const float cc[8] = {c0.x, c0.y, c0.z, c0.w, c1.x, c1.y, c1.z, c1.w}, ss[8] = {s0.x, s0.y, s0.z, s0.w, s1.x, s1.y, s1.z, s1.w};
;       float o1[8], o2[8];
; #pragma unroll
;       for (int j = 0; j < 8; ++j) { const float a = bf2f(x1[j]), b = bf2f(x2[j]); o1[j] = a * cc[j] - b * ss[j]; o2[j] = a * ss[j] + b * cc[j]; }
;       qr[8 + f] = pack8(o1); qr[10 + f] = pack8(o2);
;     } }
;   int voK0, voV0, voR;
;   { const int row = tid >> 4, cch = (tid & 15) ^ (row & 7); voK0 = row * 4096 + cch * 16; }
;   { const int row = tid >> 3, cch = (tid & 7) ^ ((row >> 1) & 7); voR = row * 128 + cch * 16; }
;   { const int sub = tid >> 5, wi = tid & 31, kk = (sub >> 2) * 8 + (wi >> 2), c = (sub & 3) * 32 + (wi & 3) * 8;
;     const int k = (kk & ~0xC) | ((kk & 4) << 1) | ((kk & 8) >> 1); voV0 = k * 4096 + c * 2; }
;   const char* Kb = (const char*)Kh; const char* Vb = (const char*)Vh; const char* Rb = (const char*)Rh;
;     ...
;   const int vb0 = (int)(uintptr_t)lds + v_rd_base(lane);
;   int ko[4], ro[4];
; #pragma unroll
;   for (int i = 0; i < 4; ++i) { ko[i] = r32 * 256 + ((i * 32 + hi * 16) ^ ((r32 & 7) << 4)); ro[i] = r32 * 128 + ((i * 32 + hi * 16) ^ (((r32 >> 1) & 7) << 4)); }
;   f32x16 pA0, pA1, pB0, pB1; float mnA, mnB, alA, alB; bf16x8 pa0, pa1, pa2, pa3; const int NT = seq / 64;
;   __syncthreads();
;   DMA(0, 0); DMA(1, 1); VWAIT(); __syncthreads();
	v_lshlrev_b32_e32 v1, 16, v2
	s_waitcnt vmcnt(4)
	v_lshlrev_b32_e32 v0, 16, v6
	s_waitcnt vmcnt(3)
	v_mov_b32_e32 v26, v10
	s_waitcnt vmcnt(2)
	v_mov_b32_e32 v27, v14
	v_mov_b32_e32 v28, v14
	v_mov_b32_e32 v29, v10
	v_pk_mul_f32 v[26:27], v[26:27], v[0:1]
	v_pk_mul_f32 v[0:1], v[28:29], v[0:1]
	v_and_b32_e32 v30, 0xffff0000, v6
	v_mov_b32_e32 v34, v12
	v_mov_b32_e32 v35, v16
	v_mov_b32_e32 v36, v16
	v_mov_b32_e32 v37, v12
	v_sub_f32_e32 v6, v27, v26
	v_add_f32_e32 v26, v0, v1
	v_and_b32_e32 v1, 0xffff0000, v3
	v_and_b32_e32 v0, 0xffff0000, v7
	v_mov_b32_e32 v16, v13
	v_mov_b32_e32 v12, v17
	v_and_b32_e32 v31, 0xffff0000, v2
	v_lshlrev_b32_e32 v33, 16, v3
	v_pk_mul_f32 v[2:3], v[16:17], v[0:1]
	v_pk_mul_f32 v[0:1], v[12:13], v[0:1]
	v_lshlrev_b32_e32 v32, 16, v7
	v_sub_f32_e32 v7, v3, v2
	v_add_f32_e32 v12, v0, v1
	v_lshlrev_b32_e32 v1, 16, v4
	v_lshlrev_b32_e32 v0, 16, v8
	s_waitcnt vmcnt(1)
	v_mov_b32_e32 v2, v18
	s_waitcnt vmcnt(0)
	v_mov_b32_e32 v3, v22
	v_pk_mul_f32 v[2:3], v[2:3], v[0:1]
	v_mov_b32_e32 v14, v11
	v_sub_f32_e32 v13, v3, v2
	v_mov_b32_e32 v2, v22
	v_mov_b32_e32 v3, v18
	v_pk_mul_f32 v[0:1], v[2:3], v[0:1]
	v_mov_b32_e32 v22, v19
	v_add_f32_e32 v16, v0, v1
	v_and_b32_e32 v1, 0xffff0000, v4
	v_and_b32_e32 v0, 0xffff0000, v8
	v_mov_b32_e32 v18, v23
	v_pk_mul_f32 v[2:3], v[22:23], v[0:1]
	v_pk_mul_f32 v[0:1], v[18:19], v[0:1]
	v_sub_f32_e32 v4, v3, v2
	v_add_f32_e32 v8, v0, v1
	v_lshlrev_b32_e32 v1, 16, v5
	v_lshlrev_b32_e32 v0, 16, v9
	v_mov_b32_e32 v2, v20
	v_mov_b32_e32 v3, v24
	v_pk_mul_f32 v[2:3], v[2:3], v[0:1]
	v_mov_b32_e32 v10, v15
	v_sub_f32_e32 v17, v3, v2
	v_mov_b32_e32 v2, v24
	v_mov_b32_e32 v3, v20
	v_pk_mul_f32 v[0:1], v[2:3], v[0:1]
	v_mov_b32_e32 v24, v21
	v_add_f32_e32 v18, v0, v1
	v_and_b32_e32 v1, 0xffff0000, v5
	v_and_b32_e32 v0, 0xffff0000, v9
	v_mov_b32_e32 v20, v25
	v_pk_mul_f32 v[2:3], v[24:25], v[0:1]
	v_pk_mul_f32 v[0:1], v[20:21], v[0:1]
	v_pk_mul_f32 v[14:15], v[14:15], v[30:31]
	v_pk_mul_f32 v[10:11], v[10:11], v[30:31]
	v_pk_mul_f32 v[28:29], v[34:35], v[32:33]
	v_pk_mul_f32 v[30:31], v[36:37], v[32:33]
	v_add_f32_e32 v0, v0, v1
	v_sub_f32_e32 v14, v15, v14
	v_add_f32_e32 v10, v10, v11
	v_sub_f32_e32 v11, v29, v28
	v_add_f32_e32 v15, v30, v31
	v_sub_f32_e32 v2, v3, v2
	v_cvt_pk_bf16_f32 v142, v6, v14
	v_cvt_pk_bf16_f32 v143, v11, v7
	v_cvt_pk_bf16_f32 v144, v13, v4
	v_cvt_pk_bf16_f32 v145, v17, v2
	v_cvt_pk_bf16_f32 v138, v26, v10
	v_cvt_pk_bf16_f32 v139, v15, v12
	v_cvt_pk_bf16_f32 v140, v16, v8
	v_cvt_pk_bf16_f32 v141, v18, v0
	v_ashrrev_i32_e32 v0, 4, v58
	v_lshrrev_b32_e32 v4, 1, v58
	v_and_b32_e32 v1, 15, v58
	v_and_b32_e32 v3, 0x60, v58
	v_and_b32_e32 v4, 8, v4
	v_lshrrev_b32_e32 v5, 1, v0
	v_bitop3_b32 v1, v0, v1, 7 bitop3:0x6c
	v_and_or_b32 v3, v82, 24, v3
	v_and_b32_e32 v60, 4, v5
	v_and_or_b32 v61, v0, -16, v4
	v_lshlrev_b32_e32 v0, 12, v0
	v_xor_b32_e32 v2, v175, v58
	v_or3_b32 v4, v61, v59, v60
	v_lshlrev_b32_e32 v3, 1, v3
	v_lshl_or_b32 v48, v1, 4, v0
	v_and_b32_e32 v0, 0xffffff80, v175
	v_and_or_b32 v50, v2, s2, v0
	v_lshl_or_b32 v0, v4, 12, v3
	v_mov_b32_e32 v1, v97
	v_lshl_add_u64 v[52:53], s[44:45], 0, v[0:1]
	v_readfirstlane_b32 s2, v178
	v_add_u32_e32 v2, 0x2000, v178
	v_lshl_add_u64 v[0:1], v[52:53], 0, s[4:5]
	s_mov_b32 m0, s2
	v_readfirstlane_b32 s2, v2
	s_barrier
	global_load_lds_dwordx4 v[0:1], off
	v_lshl_add_u64 v[0:1], v[52:53], 0, s[12:13]
	s_mov_b32 m0, s2
	v_add_u32_e32 v2, 0x6000, v178
	global_load_lds_dwordx4 v[0:1], off
	v_add_u32_e32 v0, 0x4000, v178
	v_lshl_add_u64 v[54:55], s[44:45], 0, v[48:49]
	v_readfirstlane_b32 s2, v0
	s_mov_b32 m0, s2
	s_mov_b64 s[12:13], 0x20000
	v_readfirstlane_b32 s2, v2
	global_load_lds_dwordx4 v48, s[44:45]
	v_lshl_add_u64 v[0:1], v[54:55], 0, s[12:13]
	s_mov_b32 m0, s2
	v_add_u32_e32 v2, 0xa000, v178
	global_load_lds_dwordx4 v[0:1], off
	v_add_u32_e32 v0, 0x8000, v178
	s_mov_b64 s[12:13], 0x40100
	v_readfirstlane_b32 s2, v0
	s_mov_b32 m0, s2
	v_readfirstlane_b32 s2, v2
	v_add_u32_e32 v2, 0xc000, v178
	global_load_lds_dwordx4 v50, s[36:37]
	v_lshl_add_u64 v[0:1], v[52:53], 0, s[12:13]
	s_mov_b32 m0, s2
	s_mov_b64 s[12:13], 0x60100
	v_readfirstlane_b32 s2, v2
	v_add_u32_e32 v2, 0xe000, v178
	global_load_lds_dwordx4 v[0:1], off
	v_lshl_add_u64 v[0:1], v[52:53], 0, s[12:13]
	s_mov_b32 m0, s2
	s_mov_b64 s[12:13], 0x40000
	v_readfirstlane_b32 s2, v2
	v_add_u32_e32 v2, 0x10000, v178
	global_load_lds_dwordx4 v[0:1], off
	v_lshl_add_u64 v[0:1], v[54:55], 0, s[12:13]
	s_mov_b32 m0, s2
	s_mov_b64 s[12:13], 0x60000
	v_readfirstlane_b32 s2, v2
	v_add_u32_e32 v2, 0x12000, v178
	v_lshl_add_u64 v[56:57], s[36:37], 0, v[50:51]
	global_load_lds_dwordx4 v[0:1], off
	v_lshl_add_u64 v[0:1], v[54:55], 0, s[12:13]
	s_mov_b32 m0, s2
	s_mov_b64 s[12:13], 0x2000
	v_readfirstlane_b32 s2, v2
	global_load_lds_dwordx4 v[0:1], off
	v_lshl_add_u64 v[0:1], v[56:57], 0, s[12:13]
	s_mov_b32 m0, s2
	v_add_u32_e32 v32, 16, v176
	global_load_lds_dwordx4 v[0:1], off
	s_waitcnt vmcnt(0)
	s_waitcnt vmcnt(0) lgkmcnt(0)
	s_barrier
; DI int v_rd_base(int lane) { return ((lane & 3) << 3) | (((lane >> 2) & 3) << 6) | (((lane >> 4) & 1) << 5) | (((lane >> 5) & 1) << 8); }
; #define QK_FENCE() __builtin_amdgcn_sched_barrier(0x406)
; #define VWAIT() asm volatile("s_waitcnt vmcnt(0)" ::: "memory")
; DI void qkt12(f32x16& p0, f32x16& p1, const char* Kt, const char* Rt, const int* ko, const int* ro, const bf16x8* qr) {
;   { const f32x16 z = {0.f, 0.f, 0.f, 0.f, 0.f, 0.f, 0.f, 0.f, 0.f, 0.f, 0.f, 0.f, 0.f, 0.f, 0.f, 0.f}; p0 = z; p1 = z; }
;   const char* kp[4] = {Kt + ko[0], Kt + ko[1], Kt + ko[2], Kt + ko[3]};
;   const char* rp[4] = {Rt + ro[0], Rt + ro[1], Rt + ro[2], Rt + ro[3]};
;   bf16x8 ka[2], kb[2];
;   ka[0] = *reinterpret_cast<const bf16x8*>(kp[0]); kb[0] = *reinterpret_cast<const bf16x8*>(kp[0] + 8192);
; #pragma unroll
;   for (int d0 = 0; d0 < 12; ++d0) {
;     if (d0 + 1 < 12) { const int d1 = d0 + 1;
;       if (d1 < 8) { ka[d1 & 1] = *reinterpret_cast<const bf16x8*>(kp[d1 & 3] + (d1 >> 2) * 128); kb[d1 & 1] = *reinterpret_cast<const bf16x8*>(kp[d1 & 3] + (d1 >> 2) * 128 + 8192); }
;       else { ka[d1 & 1] = *reinterpret_cast<const bf16x8*>(rp[d1 - 8]); kb[d1 & 1] = *reinterpret_cast<const bf16x8*>(rp[d1 - 8] + 4096); } }
;     QK_FENCE();
;     p0 = __builtin_amdgcn_mfma_f32_32x32x16_bf16(ka[d0 & 1], qr[d0], p0, 0, 0, 0);
;     p1 = __builtin_amdgcn_mfma_f32_32x32x16_bf16(kb[d0 & 1], qr[d0], p1, 0, 0, 0);
;     QK_FENCE();
;   }
; DI void attn_item_dma(const u16* Qb, const u16* Kh, const u16* Vh, const u16* Rh, u16* Ob, int seq, const float* rope, int pos0, char* lds) {
;     ...
;   const int vb0 = (int)(uintptr_t)lds + v_rd_base(lane);
;   int ko[4], ro[4];
; #pragma unroll
;   for (int i = 0; i < 4; ++i) { ko[i] = r32 * 256 + ((i * 32 + hi * 16) ^ ((r32 & 7) << 4)); ro[i] = r32 * 128 + ((i * 32 + hi * 16) ^ (((r32 >> 1) & 7) << 4)); }
;   f32x16 pA0, pA1, pB0, pB1; float mnA, mnB, alA, alB; bf16x8 pa0, pa1, pa2, pa3; const int NT = seq / 64;
;   __syncthreads();
;   DMA(0, 0); DMA(1, 1); VWAIT(); __syncthreads();
;   qkt12(pA0, pA1, lds + 16384, lds + 32768, ko, ro, qr); partialSM(pA0, pA1, m_reg, mnA, alA);
;   if (2 < NT) DMA(2, 2);
	ds_read_b128 v[0:3], v32 offset:16384
	ds_read_b128 v[4:7], v32 offset:24576
	ds_read_b128 v[8:11], v76 offset:16384
	ds_read_b128 v[12:15], v76 offset:24576
	s_waitcnt lgkmcnt(3)
	v_mfma_f32_32x32x16_bf16 v[16:31], v[0:3], v[134:137], 0
	ds_read_b128 v[62:65], v32 offset:16512
	ds_read_b128 v[0:3], v32 offset:24704
	s_add_i32 s2, 16, 0x1e000
	s_cmp_lg_u32 16, -1
	s_mov_b64 s[36:37], 0x80100
	s_mov_b32 s12, 4
	s_waitcnt lgkmcnt(4)
	v_mfma_f32_32x32x16_bf16 v[32:47], v[4:7], v[134:137], 0
	ds_read_b128 v[4:7], v85 offset:16384
	ds_read_b128 v[66:69], v85 offset:24576
	ds_read_b128 v[70:73], v76 offset:16512
	s_waitcnt lgkmcnt(6)
	v_mfma_f32_32x32x16_bf16 v[16:31], v[8:11], v[130:133], v[16:31]
	ds_read_b128 v[8:11], v76 offset:24704
	s_waitcnt lgkmcnt(6)
	v_mfma_f32_32x32x16_bf16 v[32:47], v[12:15], v[130:133], v[32:47]
	ds_read_b128 v[12:15], v87 offset:16384
	ds_read_b128 v[74:77], v87 offset:24576
	ds_read_b128 v[78:81], v85 offset:16512
	s_waitcnt lgkmcnt(6)
	v_mfma_f32_32x32x16_bf16 v[16:31], v[4:7], v[126:129], v[16:31]
	ds_read_b128 v[4:7], v85 offset:24704
	s_waitcnt lgkmcnt(6)
	v_mfma_f32_32x32x16_bf16 v[32:47], v[66:69], v[126:129], v[32:47]
	ds_read_b128 v[66:69], v87 offset:16512
	s_waitcnt lgkmcnt(4)
	v_mfma_f32_32x32x16_bf16 v[16:31], v[12:15], v[114:117], v[16:31]
	ds_read_b128 v[12:15], v87 offset:24704
	s_waitcnt lgkmcnt(4)
	v_mfma_f32_32x32x16_bf16 v[32:47], v[74:77], v[114:117], v[32:47]
	v_mfma_f32_32x32x16_bf16 v[16:31], v[62:65], v[110:113], v[16:31]
	v_lshlrev_b32_e32 v62, 7, v170
	v_and_b32_e32 v63, 0x70, v82
	v_bitop3_b32 v182, v96, v62, v63 bitop3:0xde
	v_bitop3_b32 v183, v83, v62, v63 bitop3:0xde
	v_bitop3_b32 v184, v84, v62, v63 bitop3:0xde
	v_bitop3_b32 v185, v86, v62, v63 bitop3:0xde
	v_mfma_f32_32x32x16_bf16 v[32:47], v[0:3], v[110:113], v[32:47]
	v_mfma_f32_32x32x16_bf16 v[16:31], v[70:73], v[106:109], v[16:31]
	v_mfma_f32_32x32x16_bf16 v[32:47], v[8:11], v[106:109], v[32:47]
	s_waitcnt lgkmcnt(3)
	v_mfma_f32_32x32x16_bf16 v[16:31], v[78:81], v[102:105], v[16:31]
	s_waitcnt lgkmcnt(2)
	v_mfma_f32_32x32x16_bf16 v[32:47], v[4:7], v[102:105], v[32:47]
	v_add_u32_e32 v4, 16, v182
	ds_read_b128 v[0:3], v4 offset:32768
	ds_read_b128 v[4:7], v4 offset:36864
	s_waitcnt lgkmcnt(3)
	v_mfma_f32_32x32x16_bf16 v[16:31], v[66:69], v[98:101], v[16:31]
	v_and_b32_e32 v66, 63, v58
	v_lshlrev_b32_e32 v67, 3, v66
	v_lshlrev_b32_e32 v68, 1, v58
	s_waitcnt lgkmcnt(2)
	v_mfma_f32_32x32x16_bf16 v[32:47], v[12:15], v[98:101], v[32:47]
	v_add_u32_e32 v12, 16, v183
	ds_read_b128 v[8:11], v12 offset:32768
	ds_read_b128 v[12:15], v12 offset:36864
	s_waitcnt lgkmcnt(3)
	v_mfma_f32_32x32x16_bf16 v[16:31], v[0:3], v[122:125], v[16:31]
	s_waitcnt lgkmcnt(2)
	v_mfma_f32_32x32x16_bf16 v[32:47], v[4:7], v[122:125], v[32:47]
	v_add_u32_e32 v4, 16, v184
	ds_read_b128 v[0:3], v4 offset:32768
	ds_read_b128 v[4:7], v4 offset:36864
	s_waitcnt lgkmcnt(3)
	v_mfma_f32_32x32x16_bf16 v[16:31], v[8:11], v[142:145], v[16:31]
	v_and_b32_e32 v8, 0x3fffffc0, v58
	v_lshl_add_u32 v147, v8, 2, s2
	v_and_b32_e32 v8, 0xc0, v175
	s_cselect_b32 s2, 16, 0
	v_lshl_add_u32 v172, v170, 2, v147
	s_waitcnt lgkmcnt(2)
	v_mfma_f32_32x32x16_bf16 v[32:47], v[12:15], v[142:145], v[32:47]
	v_add_u32_e32 v14, 16, v185
	v_and_or_b32 v12, v67, 24, v8
	ds_read_b128 v[8:11], v14 offset:32768
	ds_read_b128 v[62:65], v14 offset:36864
	v_and_b32_e32 v13, 32, v68
	s_waitcnt lgkmcnt(3)
	v_mfma_f32_32x32x16_bf16 v[16:31], v[0:3], v[118:121], v[16:31]
	v_and_b32_e32 v0, 0x100, v67
	v_or3_b32 v0, v12, v13, v0
	v_add_u32_e32 v174, s2, v0
	s_add_i32 s2, 16, 0x14000
	s_waitcnt lgkmcnt(2)
	v_mfma_f32_32x32x16_bf16 v[32:47], v[4:7], v[118:121], v[32:47]
	s_waitcnt lgkmcnt(1)
	v_mfma_f32_32x32x16_bf16 v[16:31], v[8:11], v[138:141], v[16:31]
	v_mov_b64_e32 v[0:1], s[84:85]
	v_mov_b64_e32 v[14:15], s[98:99]
	v_mov_b64_e32 v[2:3], s[86:87]
	v_mov_b64_e32 v[4:5], s[88:89]
	v_mov_b64_e32 v[6:7], s[90:91]
	v_mov_b64_e32 v[8:9], s[92:93]
	v_mov_b64_e32 v[10:11], s[94:95]
	s_waitcnt lgkmcnt(0)
	v_mfma_f32_32x32x16_bf16 v[32:47], v[62:65], v[138:141], v[32:47]
	s_nop 2
	v_max_f32_e32 v62, v17, v17
	v_max_f32_e32 v63, v16, v16
	v_max_f32_e32 v62, v63, v62
	v_max3_f32 v62, v62, v18, v19
	v_max3_f32 v62, v62, v20, v21
	v_max3_f32 v62, v62, v22, v23
	v_max3_f32 v62, v62, v24, v25
	v_max3_f32 v62, v62, v26, v27
	v_max3_f32 v62, v62, v28, v29
	v_max3_f32 v62, v62, v30, v31
	v_max3_f32 v62, v62, v32, v33
	v_max3_f32 v62, v62, v34, v35
	v_max3_f32 v62, v62, v36, v37
	v_max3_f32 v62, v62, v38, v39
	v_max3_f32 v62, v62, v40, v41
	v_add_u32_e32 v65, s2, v175
	v_max3_f32 v62, v62, v42, v43
	v_readfirstlane_b32 s2, v65
	v_max3_f32 v64, v62, v44, v45
	v_lshl_add_u64 v[62:63], v[52:53], 0, s[36:37]
	s_mov_b32 m0, s2
	s_mov_b64 s[36:37], 0xa0100
	global_load_lds_dwordx4 v[62:63], off
	v_add_u32_e32 v62, 0x2000, v65
	v_lshl_add_u64 v[52:53], v[52:53], 0, s[36:37]
	v_readfirstlane_b32 s2, v62
	v_add_u32_e32 v62, 0x4000, v65
	s_mov_b32 m0, s2
	v_readfirstlane_b32 s2, v62
	global_load_lds_dwordx4 v[52:53], off
	v_lshl_add_u64 v[52:53], v[54:55], 0, s[66:67]
	s_mov_b32 m0, s2
	s_mov_b64 s[36:37], 0xa0000
	global_load_lds_dwordx4 v[52:53], off
	v_lshl_add_u64 v[52:53], v[54:55], 0, s[36:37]
	v_add_u32_e32 v54, 0x6000, v65
	v_mov_b64_e32 v[12:13], s[96:97]
	v_readfirstlane_b32 s2, v54
	v_add_u32_e32 v54, 0x8000, v65
	s_mov_b32 m0, s2
	v_readfirstlane_b32 s2, v54
	global_load_lds_dwordx4 v[52:53], off
	v_lshl_add_u64 v[52:53], v[56:57], 0, s[68:69]
	s_mov_b32 m0, s2
	s_movk_i32 s96, 0x7b00
	global_load_lds_dwordx4 v[52:53], off
	v_max3_f32 v52, v64, v46, v47
	v_mov_b32_e32 v53, v52
	s_nop 1
	v_permlane32_swap_b32_e32 v52, v53
; #define SBAR() __builtin_amdgcn_sched_barrier(0)
; DI void partialSM(f32x16& p0, f32x16& p1, float& m_reg, float& mn, float& alpha) {
;   constexpr float C = ATT_SCALE * 1.4426950408889634f;
;   float pmax = p0[0];
; #pragma unroll
;   for (int r = 1; r < 16; ++r) pmax = fmaxf(pmax, p0[r]);
; #pragma unroll
;   for (int r = 0; r < 16; ++r) pmax = fmaxf(pmax, p1[r]);
;   { auto rr = __builtin_amdgcn_permlane32_swap(__float_as_uint(pmax), __float_as_uint(pmax), false, false);
;     pmax = fmaxf(__uint_as_float(rr[0]), __uint_as_float(rr[1])); }
;   if (__builtin_expect(__all(pmax - m_reg <= ATT_THR / ATT_SCALE), 1)) { mn = m_reg; alpha = 1.f; }
;   else { mn = fmaxf(m_reg, pmax); alpha = __builtin_amdgcn_exp2f((m_reg - mn) * C); m_reg = mn; }
;   const float mnC = -mn * C;
; #pragma unroll
;   for (int r = 0; r < 16; ++r) p0[r] = fmaf(p0[r], C, mnC);
; #pragma unroll
;   for (int r = 0; r < 16; ++r) p1[r] = fmaf(p1[r], C, mnC);
; #pragma unroll
;   for (int r = 0; r < 16; ++r) p0[r] = __builtin_amdgcn_exp2f(p0[r]);
; }
; DI void attn_item_dma(const u16* Qb, const u16* Kh, const u16* Vh, const u16* Rh, u16* Ob, int seq, const float* rope, int pos0, char* lds) {
;     ...
;   for (int j = 1; j + 1 < NT; j += 2) {
;     const int sp = PRV(sj), sn = NXT(sj);
;     SBAR(); qkt12(pB0, pB1, lds + sj * STG + 16384, lds + sj * STG + 32768, ko, ro, qr);
;     finishSM(pA0, pA1, alA, l_reg, pa0, pa1, pa2, pa3); SBAR();
	v_max_f32_e32 v53, v53, v53
	v_max_f32_e32 v52, v52, v52
	v_max_f32_e32 v52, v52, v53
	v_add_f32_e32 v53, 0x7149f2ca, v52
	v_cmp_ge_f32_e32 vcc, s65, v53
	s_cmp_eq_u64 vcc, exec
	v_max_f32_e32 v52, 0xf149f2ca, v52
	s_cselect_b64 vcc, -1, 0
	v_mov_b32_e32 v53, 0xf149f2ca
	v_cndmask_b32_e32 v187, v52, v53, vcc
	v_sub_f32_e32 v54, 0xf149f2ca, v52
	v_mul_f32_e32 v52, 0xbdd53b94, v187
	v_fmamk_f32 v200, v16, 0x3dd53b94, v52
	v_fmamk_f32 v202, v17, 0x3dd53b94, v52
	v_fmamk_f32 v201, v18, 0x3dd53b94, v52
	v_fmamk_f32 v204, v19, 0x3dd53b94, v52
	v_fmamk_f32 v203, v20, 0x3dd53b94, v52
	v_fmamk_f32 v206, v21, 0x3dd53b94, v52
	v_fmamk_f32 v205, v22, 0x3dd53b94, v52
	v_fmamk_f32 v207, v23, 0x3dd53b94, v52
	v_fmamk_f32 v192, v24, 0x3dd53b94, v52
	v_fmamk_f32 v194, v25, 0x3dd53b94, v52
	v_fmamk_f32 v193, v26, 0x3dd53b94, v52
	v_fmamk_f32 v196, v27, 0x3dd53b94, v52
	v_fmamk_f32 v195, v28, 0x3dd53b94, v52
	v_mul_f32_e32 v54, 0x3dd53b94, v54
	v_fmamk_f32 v198, v29, 0x3dd53b94, v52
	v_exp_f32_e32 v54, v54
	v_fmamk_f32 v197, v30, 0x3dd53b94, v52
	s_add_u32 s42, s26, s42
	v_pk_fma_f32 v[158:159], v[46:47], s[70:71], v[52:53] op_sel_hi:[1,0,0]
	v_pk_fma_f32 v[164:165], v[44:45], s[70:71], v[52:53] op_sel_hi:[1,0,0]
	v_pk_fma_f32 v[168:169], v[42:43], s[70:71], v[52:53] op_sel_hi:[1,0,0]
	v_pk_fma_f32 v[154:155], v[40:41], s[70:71], v[52:53] op_sel_hi:[1,0,0]
	v_pk_fma_f32 v[156:157], v[38:39], s[70:71], v[52:53] op_sel_hi:[1,0,0]
	v_pk_fma_f32 v[160:161], v[36:37], s[70:71], v[52:53] op_sel_hi:[1,0,0]
	v_pk_fma_f32 v[162:163], v[34:35], s[70:71], v[52:53] op_sel_hi:[1,0,0]
	v_pk_fma_f32 v[166:167], v[32:33], s[70:71], v[52:53] op_sel_hi:[1,0,0]
	v_fmamk_f32 v199, v31, 0x3dd53b94, v52
	s_addc_u32 s43, s27, s43
	s_or_b32 s2, s38, s6
	v_or3_b32 v16, v61, v60, v59
	v_and_b32_e32 v18, 3, v58
	v_lshlrev_b32_e32 v16, 12, v16
	v_and_b32_e32 v17, 0xc0, v68
	v_lshlrev_b32_e32 v18, 4, v18
	s_add_u32 s6, s26, s2
	v_or3_b32 v16, v16, v17, v18
	v_mov_b32_e32 v17, v97
	s_addc_u32 s7, s27, s39
	v_cndmask_b32_e64 v186, v54, 1.0, vcc
	v_lshl_add_u64 v[148:149], s[42:43], 0, v[50:51]
	v_lshl_add_u64 v[150:151], s[6:7], 0, v[16:17]
	v_lshl_add_u64 v[152:153], s[6:7], 0, v[48:49]
	v_mov_b64_e32 v[62:63], v[14:15]
	v_mov_b64_e32 v[46:47], v[14:15]
	v_mov_b64_e32 v[30:31], v[14:15]
	s_movk_i32 s95, 0x104
	v_cmp_gt_u32_e64 s[36:37], 32, v66
	v_mov_b64_e32 v[60:61], v[12:13]
	v_mov_b64_e32 v[58:59], v[10:11]
	v_mov_b64_e32 v[56:57], v[8:9]
	v_mov_b64_e32 v[54:55], v[6:7]
	v_mov_b64_e32 v[52:53], v[4:5]
	v_mov_b64_e32 v[50:51], v[2:3]
	v_mov_b64_e32 v[48:49], v[0:1]
	v_mov_b64_e32 v[44:45], v[12:13]
	v_mov_b64_e32 v[42:43], v[10:11]
	v_mov_b64_e32 v[40:41], v[8:9]
	v_mov_b64_e32 v[38:39], v[6:7]
	v_mov_b64_e32 v[36:37], v[4:5]
	v_mov_b64_e32 v[34:35], v[2:3]
	v_mov_b64_e32 v[32:33], v[0:1]
	v_mov_b64_e32 v[28:29], v[12:13]
	v_mov_b64_e32 v[26:27], v[10:11]
	v_mov_b64_e32 v[24:25], v[8:9]
	v_mov_b64_e32 v[22:23], v[6:7]
	v_mov_b64_e32 v[20:21], v[4:5]
	v_mov_b64_e32 v[18:19], v[2:3]
	v_mov_b64_e32 v[16:17], v[0:1]
	v_readfirstlane_b32 s2, v232
	s_cmp_lt_u32 s2, 0x100
	s_cbranch_scc1 .Lattn_noprio
	s_setprio 1
.Lattn_noprio:
.LBB0_122:
	v_sub_co_u32_e64 v64, s[6:7], s61, 1
	s_and_b64 s[6:7], s[6:7], exec
	v_readfirstlane_b32 s2, v64
	s_cselect_b32 s13, 2, s2
	s_mul_i32 s42, s61, 0xa000
	s_add_i32 s45, s42, 16
	v_add_u32_e32 v177, s45, v176
	ds_read_b128 v[64:67], v177 offset:16384
	v_add_u32_e32 v220, s45, v179
	ds_read_b128 v[68:71], v177 offset:24576
	ds_read_b128 v[188:191], v220 offset:16384
	ds_read_b128 v[208:211], v220 offset:24576
	v_add_u32_e32 v221, s45, v180
	v_add_u32_e32 v222, s45, v181
	v_exp_f32_e32 v200, v200
	v_exp_f32_e32 v202, v202
	v_exp_f32_e32 v201, v201
	v_exp_f32_e32 v204, v204
	v_exp_f32_e32 v203, v203
	v_exp_f32_e32 v206, v206
	v_exp_f32_e32 v205, v205
	v_exp_f32_e32 v207, v207
	v_exp_f32_e32 v192, v192
	v_exp_f32_e32 v194, v194
	v_exp_f32_e32 v193, v193
	v_exp_f32_e32 v196, v196
	v_exp_f32_e32 v195, v195
	v_exp_f32_e32 v198, v198
	v_exp_f32_e32 v197, v197
	v_exp_f32_e32 v199, v199
	v_exp_f32_e32 v166, v166
	s_waitcnt lgkmcnt(3)
	v_mfma_f32_32x32x16_bf16 v[80:95], v[64:67], v[134:137], 0
	v_exp_f32_e32 v167, v167
	v_exp_f32_e32 v163, v163
	v_exp_f32_e32 v168, v168
	v_mfma_f32_32x32x16_bf16 v[64:79], v[68:71], v[134:137], 0
	ds_read_b128 v[212:215], v221 offset:16384
	ds_read_b128 v[216:219], v221 offset:24576
	v_exp_f32_e32 v169, v169
	v_exp_f32_e32 v235, v162
	v_exp_f32_e32 v237, v164
	s_waitcnt lgkmcnt(2)
	v_mfma_f32_32x32x16_bf16 v[64:79], v[208:211], v[130:133], v[64:79]
	s_add_i32 s2, s42, 0xa000
	s_cmp_lg_u32 s61, 2
	s_cselect_b32 s2, s2, 0
	v_add_u32_e32 v240, s2, v178
	s_add_u32 s0, s82, 0x1bbc0100
	s_addc_u32 s1, s83, 0
	v_lshl_add_u64 v[238:239], v[150:151], 0, s[0:1]
	v_readfirstlane_b32 s2, v240
	s_mov_b32 m0, s2
	v_exp_f32_e32 v241, v165
	global_load_lds_dwordx4 v[238:239], off
	v_mfma_f32_32x32x16_bf16 v[80:95], v[188:191], v[130:133], v[80:95]
	ds_read_b128 v[188:191], v222 offset:16384
	ds_read_b128 v[208:211], v222 offset:24576
	v_exp_f32_e32 v243, v158
	v_exp_f32_e32 v244, v159
	v_exp_f32_e32 v245, v154
	s_waitcnt lgkmcnt(2)
	v_mfma_f32_32x32x16_bf16 v[64:79], v[216:219], v[126:129], v[64:79]
	v_add_f32_e32 v154, 0, v200
	v_add_f32_e32 v154, v202, v154
	v_add_f32_e32 v154, v201, v154
	v_add_f32_e32 v154, v204, v154
	v_add_f32_e32 v154, v203, v154
	v_add_f32_e32 v154, v206, v154
	v_mfma_f32_32x32x16_bf16 v[80:95], v[212:215], v[126:129], v[80:95]
	ds_read_b128 v[212:215], v177 offset:16512
	ds_read_b128 v[216:219], v177 offset:24704
	v_add_u32_e32 v177, s45, v182
	v_add_f32_e32 v154, v205, v154
	v_add_f32_e32 v154, v207, v154
	v_add_f32_e32 v154, v192, v154
	v_add_f32_e32 v154, v194, v154
	v_add_f32_e32 v154, v193, v154
	s_waitcnt lgkmcnt(2)
; #define QK_FENCE() __builtin_amdgcn_sched_barrier(0x406)
; DI void finishSM(f32x16& p0, f32x16& p1, float alpha, float& l_reg, bf16x8& pa0, bf16x8& pa1, bf16x8& pa2, bf16x8& pa3) {
; #pragma unroll
;   for (int r = 0; r < 16; ++r) p1[r] = __builtin_amdgcn_exp2f(p1[r]);
;   float ps = 0;
; #pragma unroll
;   for (int r = 0; r < 16; ++r) ps += p0[r];
; #pragma unroll
;   for (int r = 0; r < 16; ++r) ps += p1[r];
;   { auto rr = __builtin_amdgcn_permlane32_swap(__float_as_uint(ps), __float_as_uint(ps), false, false);
;     ps = __uint_as_float(rr[0]) + __uint_as_float(rr[1]); }
;   l_reg = l_reg * alpha + ps;
;     ...
;   PK4(p0, 0, pa0); PK4(p0, 8, pa1); PK4(p1, 0, pa2); PK4(p1, 8, pa3);
; DI void qkt12(f32x16& p0, f32x16& p1, const char* Kt, const char* Rt, const int* ko, const int* ro, const bf16x8* qr) {
;   { const f32x16 z = {0.f, 0.f, 0.f, 0.f, 0.f, 0.f, 0.f, 0.f, 0.f, 0.f, 0.f, 0.f, 0.f, 0.f, 0.f, 0.f}; p0 = z; p1 = z; }
;   const char* kp[4] = {Kt + ko[0], Kt + ko[1], Kt + ko[2], Kt + ko[3]};
;   const char* rp[4] = {Rt + ro[0], Rt + ro[1], Rt + ro[2], Rt + ro[3]};
;   bf16x8 ka[2], kb[2];
;   ka[0] = *reinterpret_cast<const bf16x8*>(kp[0]); kb[0] = *reinterpret_cast<const bf16x8*>(kp[0] + 8192);
; #pragma unroll
;   for (int d0 = 0; d0 < 12; ++d0) {
;     if (d0 + 1 < 12) { const int d1 = d0 + 1;
;       if (d1 < 8) { ka[d1 & 1] = *reinterpret_cast<const bf16x8*>(kp[d1 & 3] + (d1 >> 2) * 128); kb[d1 & 1] = *reinterpret_cast<const bf16x8*>(kp[d1 & 3] + (d1 >> 2) * 128 + 8192); }
;       else { ka[d1 & 1] = *reinterpret_cast<const bf16x8*>(rp[d1 - 8]); kb[d1 & 1] = *reinterpret_cast<const bf16x8*>(rp[d1 - 8] + 4096); } }
;     QK_FENCE();
;     p0 = __builtin_amdgcn_mfma_f32_32x32x16_bf16(ka[d0 & 1], qr[d0], p0, 0, 0, 0);
;     p1 = __builtin_amdgcn_mfma_f32_32x32x16_bf16(kb[d0 & 1], qr[d0], p1, 0, 0, 0);
;     QK_FENCE();
;   }
	v_mfma_f32_32x32x16_bf16 v[64:79], v[208:211], v[114:117], v[64:79]
	v_add_u32_e32 v242, 0x2000, v240
	s_add_u32 s0, s82, 0x1bbe0100
	s_addc_u32 s1, s83, 0
	v_lshl_add_u64 v[238:239], v[150:151], 0, s[0:1]
	v_readfirstlane_b32 s2, v242
	s_mov_b32 m0, s2
	v_add_f32_e32 v154, v196, v154
	global_load_lds_dwordx4 v[238:239], off
	v_add_f32_e32 v154, v195, v154
	v_add_f32_e32 v154, v198, v154
	v_mfma_f32_32x32x16_bf16 v[80:95], v[188:191], v[114:117], v[80:95]
	ds_read_b128 v[188:191], v220 offset:16512
	ds_read_b128 v[208:211], v220 offset:24704
	v_add_f32_e32 v154, v197, v154
	v_add_f32_e32 v154, v199, v154
	v_exp_f32_e32 v246, v160
	v_add_f32_e32 v154, v166, v154
	s_waitcnt lgkmcnt(2)
	v_mfma_f32_32x32x16_bf16 v[64:79], v[216:219], v[110:113], v[64:79]
	v_exp_f32_e32 v248, v161
	v_add_f32_e32 v154, v167, v154
	v_exp_f32_e32 v249, v156
	v_add_f32_e32 v154, v235, v154
	v_mfma_f32_32x32x16_bf16 v[80:95], v[212:215], v[110:113], v[80:95]
	ds_read_b128 v[212:215], v221 offset:16512
	ds_read_b128 v[216:219], v221 offset:24704
	v_exp_f32_e32 v250, v157
	v_add_f32_e32 v154, v163, v154
	v_add_f32_e32 v154, v246, v154
	v_exp_f32_e32 v251, v155
	s_waitcnt lgkmcnt(2)
	v_mfma_f32_32x32x16_bf16 v[64:79], v[208:211], v[106:109], v[64:79]
	v_add_u32_e32 v242, 0x4000, v240
	s_add_u32 s0, s82, 0x1bbc0000
	s_addc_u32 s1, s83, 0
	v_lshl_add_u64 v[238:239], v[152:153], 0, s[0:1]
	v_readfirstlane_b32 s2, v242
	s_mov_b32 m0, s2
	v_add_f32_e32 v154, v248, v154
	global_load_lds_dwordx4 v[238:239], off
	v_add_f32_e32 v154, v249, v154
	v_add_f32_e32 v154, v250, v154
	v_mfma_f32_32x32x16_bf16 v[80:95], v[188:191], v[106:109], v[80:95]
	ds_read_b128 v[188:191], v222 offset:16512
	ds_read_b128 v[208:211], v222 offset:24704
	v_add_f32_e32 v154, v245, v154
	v_add_f32_e32 v154, v251, v154
	v_add_f32_e32 v154, v168, v154
	v_add_f32_e32 v154, v169, v154
	v_add_f32_e32 v154, v237, v154
	v_add_f32_e32 v154, v241, v154
	s_waitcnt lgkmcnt(2)
	v_mfma_f32_32x32x16_bf16 v[64:79], v[216:219], v[102:105], v[64:79]
	v_add_f32_e32 v154, v243, v154
	v_cvt_pk_bf16_f32 v155, v201, v204
	v_cvt_pk_bf16_f32 v156, v203, v206
	v_cvt_pk_bf16_f32 v157, v205, v207
	v_cvt_pk_bf16_f32 v158, v192, v194
	v_cvt_pk_bf16_f32 v159, v193, v196
	v_mfma_f32_32x32x16_bf16 v[80:95], v[212:215], v[102:105], v[80:95]
	ds_read_b128 v[212:215], v177 offset:32768
	ds_read_b128 v[216:219], v177 offset:36864
	v_add_u32_e32 v177, s45, v183
	v_cvt_pk_bf16_f32 v160, v195, v198
	v_cvt_pk_bf16_f32 v161, v197, v199
	v_permlane32_swap_b32_e32 v155, v157
	v_permlane32_swap_b32_e32 v158, v160
	v_permlane32_swap_b32_e32 v159, v161
	s_waitcnt lgkmcnt(2)
	v_mfma_f32_32x32x16_bf16 v[64:79], v[208:211], v[98:101], v[64:79]
	v_add_u32_e32 v242, 0x6000, v240
	s_add_u32 s0, s82, 0x1bbe0000
	s_addc_u32 s1, s83, 0
	v_lshl_add_u64 v[238:239], v[152:153], 0, s[0:1]
	v_readfirstlane_b32 s2, v242
	s_mov_b32 m0, s2
	v_cvt_pk_bf16_f32 v162, v166, v167
	global_load_lds_dwordx4 v[238:239], off
	v_cvt_pk_bf16_f32 v163, v235, v163
	v_cvt_pk_bf16_f32 v164, v246, v248
	v_mfma_f32_32x32x16_bf16 v[80:95], v[188:191], v[98:101], v[80:95]
	ds_read_b128 v[188:191], v177 offset:32768
	ds_read_b128 v[208:211], v177 offset:36864
	v_add_u32_e32 v177, s45, v184
	v_cvt_pk_bf16_f32 v165, v249, v250
	v_cvt_pk_bf16_f32 v166, v245, v251
	v_cvt_pk_bf16_f32 v167, v168, v169
	v_cvt_pk_bf16_f32 v168, v237, v241
	v_cvt_pk_bf16_f32 v169, v243, v244
	s_waitcnt lgkmcnt(2)
	v_mfma_f32_32x32x16_bf16 v[64:79], v[216:219], v[122:125], v[64:79]
	v_permlane32_swap_b32_e32 v162, v164
	v_permlane32_swap_b32_e32 v163, v165
	v_permlane32_swap_b32_e32 v166, v168
	v_permlane32_swap_b32_e32 v167, v169
	v_mfma_f32_32x32x16_bf16 v[80:95], v[212:215], v[122:125], v[80:95]
	ds_read_b128 v[212:215], v177 offset:32768
	ds_read_b128 v[216:219], v177 offset:36864
	v_add_u32_e32 v177, s45, v185
	s_waitcnt lgkmcnt(2)
	v_mfma_f32_32x32x16_bf16 v[64:79], v[208:211], v[142:145], v[64:79]
	v_add_u32_e32 v242, 0x8000, v240
	s_add_u32 s0, s82, 0x1fb44000
	s_addc_u32 s1, s83, 0
	v_lshl_add_u64 v[238:239], v[148:149], 0, s[0:1]
	v_readfirstlane_b32 s2, v242
	s_mov_b32 m0, s2
	s_nop 0
	global_load_lds_dwordx4 v[238:239], off
	s_movk_i32 s0, 0x410
	s_movk_i32 s1, 0x1800
	v_mfma_f32_32x32x16_bf16 v[80:95], v[188:191], v[142:145], v[80:95]
	ds_read_b128 v[188:191], v177 offset:32768
	ds_read_b128 v[208:211], v177 offset:36864
	s_waitcnt lgkmcnt(2)
	v_mfma_f32_32x32x16_bf16 v[64:79], v[216:219], v[118:121], v[64:79]
	v_mfma_f32_32x32x16_bf16 v[80:95], v[212:215], v[118:121], v[80:95]
	s_waitcnt lgkmcnt(0)
; #define SBAR() __builtin_amdgcn_sched_barrier(0)
; template <int OFF> DI s16x4 tr_read(int vb) { s16x4 r; asm volatile("ds_read_b64_tr_b16 %0, %1 offset:%2" : "=&v"(r) : "v"(vb), "i"(OFF) : "memory"); return r; }
; DI void partialSM(f32x16& p0, f32x16& p1, float& m_reg, float& mn, float& alpha) {
;   constexpr float C = ATT_SCALE * 1.4426950408889634f;
;   float pmax = p0[0];
; #pragma unroll
;   for (int r = 1; r < 16; ++r) pmax = fmaxf(pmax, p0[r]);
; #pragma unroll
;   for (int r = 0; r < 16; ++r) pmax = fmaxf(pmax, p1[r]);
;   { auto rr = __builtin_amdgcn_permlane32_swap(__float_as_uint(pmax), __float_as_uint(pmax), false, false);
;     pmax = fmaxf(__uint_as_float(rr[0]), __uint_as_float(rr[1])); }
;   if (__builtin_expect(__all(pmax - m_reg <= ATT_THR / ATT_SCALE), 1)) { mn = m_reg; alpha = 1.f; }
;   else { mn = fmaxf(m_reg, pmax); alpha = __builtin_amdgcn_exp2f((m_reg - mn) * C); m_reg = mn; }
; template <int D0> DI void pv_one(f32x16& od, int vb, bf16x8 pa0, bf16x8 pa1, bf16x8 pa2, bf16x8 pa3) {
;   const s16x4 l0 = tr_read<v_rd_off(D0, 0, 0)>(vb), h0 = tr_read<v_rd_off(D0, 0, 1)>(vb), l1 = tr_read<v_rd_off(D0, 1, 0)>(vb), h1 = tr_read<v_rd_off(D0, 1, 1)>(vb);
;   const s16x4 l2 = tr_read<v_rd_off(D0, 2, 0)>(vb), h2 = tr_read<v_rd_off(D0, 2, 1)>(vb), l3 = tr_read<v_rd_off(D0, 3, 0)>(vb), h3 = tr_read<v_rd_off(D0, 3, 1)>(vb);
;   asm volatile("s_waitcnt lgkmcnt(0)" ::: "memory"); SBAR();
;     ...
;   od = __builtin_amdgcn_mfma_f32_32x32x16_bf16(pa0, PK(l0, h0), od, 0, 0, 0);
;   od = __builtin_amdgcn_mfma_f32_32x32x16_bf16(pa1, PK(l1, h1), od, 0, 0, 0);
;   od = __builtin_amdgcn_mfma_f32_32x32x16_bf16(pa2, PK(l2, h2), od, 0, 0, 0);
;   od = __builtin_amdgcn_mfma_f32_32x32x16_bf16(pa3, PK(l3, h3), od, 0, 0, 0);
;     ...
; }
; DI void pv_d0(f32x16* o, int vb, bf16x8 pa0, bf16x8 pa1, bf16x8 pa2, bf16x8 pa3) {
;   pv_one<0>(o[0], vb, pa0, pa1, pa2, pa3); pv_one<1>(o[1], vb, pa0, pa1, pa2, pa3); pv_one<2>(o[2], vb, pa0, pa1, pa2, pa3); pv_one<3>(o[3], vb, pa0, pa1, pa2, pa3);
	v_mfma_f32_32x32x16_bf16 v[64:79], v[208:211], v[138:141], v[64:79]
	v_mfma_f32_32x32x16_bf16 v[80:95], v[188:191], v[138:141], v[80:95]
	s_mul_i32 s44, s13, 0xa000
	v_add_u32_e32 v177, s44, v174
	ds_read_b64_tr_b16 v[190:191], v177 offset:0
	ds_read_b64_tr_b16 v[192:193], v177 offset:0x800
	ds_read_b64_tr_b16 v[194:195], v177 offset:0x1000
	ds_read_b64_tr_b16 v[196:197], v177 offset:0x1800
	ds_read_b64_tr_b16 v[198:199], v177 offset:0x2000
	v_add_f32_e32 v188, v244, v154
	v_mov_b32_e32 v189, v188
	v_cvt_pk_bf16_f32 v154, v200, v202
	ds_read_b64_tr_b16 v[200:201], v177 offset:0x2800
	ds_read_b64_tr_b16 v[202:203], v177 offset:0x3000
	ds_read_b64_tr_b16 v[204:205], v177 offset:0x3800
	v_permlane32_swap_b32_e32 v188, v189
	v_permlane32_swap_b32_e32 v154, v156
	s_waitcnt lgkmcnt(6)
	v_max_f32_e32 v235, v81, v81
	v_mfma_f32_32x32x16_bf16 v[0:15], v[154:157], v[190:193], v[0:15]
	ds_read_b64_tr_b16 v[190:191], v177 offset:0x200
	ds_read_b64_tr_b16 v[192:193], v177 offset:0xa00
	v_max_f32_e32 v237, v80, v80
	v_max_f32_e32 v235, v237, v235
	v_max3_f32 v235, v235, v82, v83
	v_max3_f32 v235, v235, v84, v85
	v_max3_f32 v235, v235, v86, v87
	v_max3_f32 v235, v235, v88, v89
	s_waitcnt lgkmcnt(6)
	v_mfma_f32_32x32x16_bf16 v[0:15], v[158:161], v[194:197], v[0:15]
	ds_read_b64_tr_b16 v[194:195], v177 offset:0x1200
	ds_read_b64_tr_b16 v[196:197], v177 offset:0x1a00
	v_max3_f32 v235, v235, v90, v91
	v_max3_f32 v235, v235, v92, v93
	v_max3_f32 v235, v235, v94, v95
	v_max3_f32 v235, v235, v64, v65
	v_max3_f32 v235, v235, v66, v67
	v_max3_f32 v235, v235, v68, v69
	s_waitcnt lgkmcnt(6)
	v_mfma_f32_32x32x16_bf16 v[0:15], v[162:165], v[198:201], v[0:15]
	ds_read_b64_tr_b16 v[198:199], v177 offset:0x2200
	ds_read_b64_tr_b16 v[200:201], v177 offset:0x2a00
	v_max3_f32 v235, v235, v70, v71
	v_max3_f32 v235, v235, v72, v73
	v_max3_f32 v235, v235, v74, v75
	v_max3_f32 v235, v235, v76, v77
	v_max3_f32 v235, v235, v78, v79
	v_mov_b32_e32 v237, v235
	s_waitcnt lgkmcnt(6)
	v_mfma_f32_32x32x16_bf16 v[0:15], v[166:169], v[202:205], v[0:15]
	ds_read_b64_tr_b16 v[202:203], v177 offset:0x3200
	ds_read_b64_tr_b16 v[204:205], v177 offset:0x3a00
	v_permlane32_swap_b32_e32 v235, v237
	v_max_f32_e32 v237, v237, v237
	v_max_f32_e32 v235, v235, v235
	s_waitcnt lgkmcnt(6)
	v_mfma_f32_32x32x16_bf16 v[48:63], v[154:157], v[190:193], v[48:63]
	ds_read_b64_tr_b16 v[190:191], v177 offset:0x400
	ds_read_b64_tr_b16 v[192:193], v177 offset:0xc00
	s_waitcnt lgkmcnt(6)
	v_mfma_f32_32x32x16_bf16 v[48:63], v[158:161], v[194:197], v[48:63]
	ds_read_b64_tr_b16 v[194:195], v177 offset:0x1400
	ds_read_b64_tr_b16 v[196:197], v177 offset:0x1c00
	s_waitcnt lgkmcnt(6)
	v_mfma_f32_32x32x16_bf16 v[48:63], v[162:165], v[198:201], v[48:63]
	ds_read_b64_tr_b16 v[198:199], v177 offset:0x2400
	ds_read_b64_tr_b16 v[200:201], v177 offset:0x2c00
	s_waitcnt lgkmcnt(6)
	v_mfma_f32_32x32x16_bf16 v[48:63], v[166:169], v[202:205], v[48:63]
	ds_read_b64_tr_b16 v[202:203], v177 offset:0x3400
	ds_read_b64_tr_b16 v[204:205], v177 offset:0x3c00
	s_waitcnt lgkmcnt(6)
	v_mfma_f32_32x32x16_bf16 v[32:47], v[154:157], v[190:193], v[32:47]
	ds_read_b64_tr_b16 v[190:191], v177 offset:0x600
	ds_read_b64_tr_b16 v[192:193], v177 offset:0xe00
	s_waitcnt lgkmcnt(6)
	v_mfma_f32_32x32x16_bf16 v[32:47], v[158:161], v[194:197], v[32:47]
	ds_read_b64_tr_b16 v[194:195], v177 offset:0x1600
	ds_read_b64_tr_b16 v[196:197], v177 offset:0x1e00
	s_waitcnt lgkmcnt(6)
	v_mfma_f32_32x32x16_bf16 v[32:47], v[162:165], v[198:201], v[32:47]
	ds_read_b64_tr_b16 v[198:199], v177 offset:0x2600
	ds_read_b64_tr_b16 v[200:201], v177 offset:0x2e00
	s_waitcnt lgkmcnt(6)
	v_mfma_f32_32x32x16_bf16 v[32:47], v[166:169], v[202:205], v[32:47]
	ds_read_b64_tr_b16 v[202:203], v177 offset:0x3600
	ds_read_b64_tr_b16 v[204:205], v177 offset:0x3e00
	s_waitcnt vmcnt(0)
	s_waitcnt lgkmcnt(0)
	s_barrier
	v_mfma_f32_32x32x16_bf16 v[16:31], v[154:157], v[190:193], v[16:31]
	v_mfma_f32_32x32x16_bf16 v[16:31], v[158:161], v[194:197], v[16:31]
	v_max_f32_e32 v160, v235, v237
	v_sub_f32_e32 v235, v160, v187
	v_mfma_f32_32x32x16_bf16 v[16:31], v[162:165], v[198:201], v[16:31]
	v_mfma_f32_32x32x16_bf16 v[16:31], v[166:169], v[202:205], v[16:31]
	v_cmp_ge_f32_e32 vcc, s65, v235
	s_cmp_eq_u64 vcc, exec
	s_waitcnt vmcnt(0)
	s_cselect_b64 s[38:39], -1, 0
	s_add_i32 s2, s12, -1
	s_cmp_ge_u32 s2, s52
	v_lshl_add_u64 v[158:159], v[150:151], 0, s[82:83]
	v_lshl_add_u64 v[156:157], v[152:153], 0, s[82:83]
	v_lshl_add_u64 v[154:155], v[148:149], 0, s[82:83]

; #define SBAR() __builtin_amdgcn_sched_barrier(0)
; #define RESC(a) do { if (__any((a) < 1.f)) { if (hi == 0) al_l[r32] = (a); asm volatile("s_waitcnt lgkmcnt(0)" ::: "memory"); \
;     _Pragma("unroll") for (int d = 0; d < 4; ++d) _Pragma("unroll") for (int r = 0; r < 16; ++r) o[d][r] *= al_l[crow(r, hi)]; } } while (0)
; #define QK_FENCE() __builtin_amdgcn_sched_barrier(0x406)
; #define RESC(a) do { if (__any((a) < 1.f)) { if (hi == 0) al_l[r32] = (a); asm volatile("s_waitcnt lgkmcnt(0)" ::: "memory"); \
;     _Pragma("unroll") for (int d = 0; d < 4; ++d) _Pragma("unroll") for (int r = 0; r < 16; ++r) o[d][r] *= al_l[crow(r, hi)]; } } while (0)
; DI void qkt12(f32x16& p0, f32x16& p1, const char* Kt, const char* Rt, const int* ko, const int* ro, const bf16x8* qr) {
;   { const f32x16 z = {0.f, 0.f, 0.f, 0.f, 0.f, 0.f, 0.f, 0.f, 0.f, 0.f, 0.f, 0.f, 0.f, 0.f, 0.f, 0.f}; p0 = z; p1 = z; }
;   const char* kp[4] = {Kt + ko[0], Kt + ko[1], Kt + ko[2], Kt + ko[3]};
;   const char* rp[4] = {Rt + ro[0], Rt + ro[1], Rt + ro[2], Rt + ro[3]};
;   bf16x8 ka[2], kb[2];
;   ka[0] = *reinterpret_cast<const bf16x8*>(kp[0]); kb[0] = *reinterpret_cast<const bf16x8*>(kp[0] + 8192);
; #pragma unroll
;   for (int d0 = 0; d0 < 12; ++d0) {
;     if (d0 + 1 < 12) { const int d1 = d0 + 1;
;       if (d1 < 8) { ka[d1 & 1] = *reinterpret_cast<const bf16x8*>(kp[d1 & 3] + (d1 >> 2) * 128); kb[d1 & 1] = *reinterpret_cast<const bf16x8*>(kp[d1 & 3] + (d1 >> 2) * 128 + 8192); }
;       else { ka[d1 & 1] = *reinterpret_cast<const bf16x8*>(rp[d1 - 8]); kb[d1 & 1] = *reinterpret_cast<const bf16x8*>(rp[d1 - 8] + 4096); } }
;     QK_FENCE();
;     p0 = __builtin_amdgcn_mfma_f32_32x32x16_bf16(ka[d0 & 1], qr[d0], p0, 0, 0, 0);
;     p1 = __builtin_amdgcn_mfma_f32_32x32x16_bf16(kb[d0 & 1], qr[d0], p1, 0, 0, 0);
;     QK_FENCE();
;   }
; DI void attn_item_dma(const u16* Qb, const u16* Kh, const u16* Vh, const u16* Rh, u16* Ob, int seq, const float* rope, int pos0, char* lds) {
;     ...
;   { const int sp = PRV(sj);
;     SBAR(); qkt12(pB0, pB1, lds + sj * STG + 16384, lds + sj * STG + 32768, ko, ro, qr);
;     finishSM(pA0, pA1, alA, l_reg, pa0, pa1, pa2, pa3); SBAR();
;     pv_d0(o, vb0 + sp * STG, pa0, pa1, pa2, pa3); partialSM(pB0, pB1, m_reg, mnB, alB);
;     RESC(alB);
;     finishSM(pB0, pB1, alB, l_reg, pa0, pa1, pa2, pa3); SBAR();
;     pv_d0(o, vb0 + sj * STG, pa0, pa1, pa2, pa3); }
.LBB0_136:
	s_setprio 0
	v_exp_f32_e32 v200, v200
	v_exp_f32_e32 v202, v202
	v_exp_f32_e32 v201, v201
	v_exp_f32_e32 v204, v204
	v_exp_f32_e32 v203, v203
	v_exp_f32_e32 v206, v206
	v_exp_f32_e32 v205, v205
	v_exp_f32_e32 v207, v207
	v_exp_f32_e32 v192, v192
	v_exp_f32_e32 v194, v194
	v_exp_f32_e32 v193, v193
	v_exp_f32_e32 v196, v196
	v_exp_f32_e32 v195, v195
	v_exp_f32_e32 v198, v198
	v_exp_f32_e32 v197, v197
	v_exp_f32_e32 v199, v199
	s_add_i32 s2, s44, 16
	v_add_u32_e32 v152, s2, v176
	v_add_u32_e32 v153, s2, v179
	v_add_u32_e32 v175, s2, v180
	v_add_u32_e32 v176, s2, v181
	ds_read_b128 v[64:67], v152 offset:16384
	ds_read_b128 v[68:71], v152 offset:24576
	ds_read_b128 v[148:151], v153 offset:16384
	ds_read_b128 v[178:181], v153 offset:24576
	s_waitcnt lgkmcnt(0)
	v_mfma_f32_32x32x16_bf16 v[80:95], v[64:67], v[134:137], 0
	v_add_u32_e32 v186, s2, v182
	v_add_u32_e32 v188, s2, v183
	v_add_u32_e32 v189, s2, v184
	v_add_u32_e32 v191, s2, v185
	v_mfma_f32_32x32x16_bf16 v[64:79], v[68:71], v[134:137], 0
	ds_read_b128 v[134:137], v175 offset:16384
	ds_read_b128 v[182:185], v175 offset:24576
	v_mfma_f32_32x32x16_bf16 v[80:95], v[148:151], v[130:133], v[80:95]
	v_mfma_f32_32x32x16_bf16 v[64:79], v[178:181], v[130:133], v[64:79]
	ds_read_b128 v[130:133], v176 offset:16384
	ds_read_b128 v[148:151], v176 offset:24576
	s_waitcnt lgkmcnt(0)
	v_mfma_f32_32x32x16_bf16 v[80:95], v[134:137], v[126:129], v[80:95]
	v_mfma_f32_32x32x16_bf16 v[64:79], v[182:185], v[126:129], v[64:79]
	ds_read_b128 v[126:129], v152 offset:16512
	ds_read_b128 v[134:137], v152 offset:24704
	v_mfma_f32_32x32x16_bf16 v[80:95], v[130:133], v[114:117], v[80:95]
	v_mfma_f32_32x32x16_bf16 v[64:79], v[148:151], v[114:117], v[64:79]
	ds_read_b128 v[114:117], v153 offset:16512
	ds_read_b128 v[130:133], v153 offset:24704
	s_waitcnt lgkmcnt(0)
	v_mfma_f32_32x32x16_bf16 v[80:95], v[126:129], v[110:113], v[80:95]
	v_mfma_f32_32x32x16_bf16 v[64:79], v[134:137], v[110:113], v[64:79]
	ds_read_b128 v[110:113], v175 offset:16512
	ds_read_b128 v[126:129], v175 offset:24704
	v_mfma_f32_32x32x16_bf16 v[80:95], v[114:117], v[106:109], v[80:95]
	v_mfma_f32_32x32x16_bf16 v[64:79], v[130:133], v[106:109], v[64:79]
	ds_read_b128 v[106:109], v176 offset:16512
	ds_read_b128 v[114:117], v176 offset:24704
	s_waitcnt lgkmcnt(0)
	v_mfma_f32_32x32x16_bf16 v[80:95], v[110:113], v[102:105], v[80:95]
	v_mfma_f32_32x32x16_bf16 v[64:79], v[126:129], v[102:105], v[64:79]
	ds_read_b128 v[102:105], v186 offset:32768
	ds_read_b128 v[110:113], v186 offset:36864
	v_mfma_f32_32x32x16_bf16 v[80:95], v[106:109], v[98:101], v[80:95]
	v_mfma_f32_32x32x16_bf16 v[64:79], v[114:117], v[98:101], v[64:79]
	ds_read_b128 v[98:101], v188 offset:32768
	ds_read_b128 v[106:109], v188 offset:36864
	v_exp_f32_e32 v114, v156
	v_exp_f32_e32 v115, v157
	v_exp_f32_e32 v116, v154
	v_exp_f32_e32 v117, v155
	s_waitcnt lgkmcnt(0)
	v_mfma_f32_32x32x16_bf16 v[80:95], v[102:105], v[122:125], v[80:95]
	v_mfma_f32_32x32x16_bf16 v[64:79], v[110:113], v[122:125], v[64:79]
	ds_read_b128 v[102:105], v189 offset:32768
	ds_read_b128 v[110:113], v189 offset:36864
	v_exp_f32_e32 v122, v158
	v_exp_f32_e32 v123, v159
	v_mfma_f32_32x32x16_bf16 v[80:95], v[98:101], v[142:145], v[80:95]
	v_mfma_f32_32x32x16_bf16 v[64:79], v[106:109], v[142:145], v[64:79]
	ds_read_b128 v[98:101], v191 offset:32768
	ds_read_b128 v[106:109], v191 offset:36864
	s_waitcnt lgkmcnt(0)
	v_mfma_f32_32x32x16_bf16 v[80:95], v[102:105], v[118:121], v[80:95]
	v_mfma_f32_32x32x16_bf16 v[64:79], v[110:113], v[118:121], v[64:79]
	v_exp_f32_e32 v110, v162
	v_exp_f32_e32 v111, v163
	v_exp_f32_e32 v112, v160
	v_exp_f32_e32 v113, v161
	v_exp_f32_e32 v118, v168
	v_exp_f32_e32 v119, v169
	v_exp_f32_e32 v120, v164
	v_mfma_f32_32x32x16_bf16 v[80:95], v[98:101], v[138:141], v[80:95]
	v_add_f32_e32 v98, 0, v200
	v_add_f32_e32 v98, v202, v98
	v_add_f32_e32 v98, v201, v98
	v_add_f32_e32 v98, v204, v98
	v_add_f32_e32 v98, v203, v98
	v_add_f32_e32 v98, v206, v98
	v_add_f32_e32 v98, v205, v98
	v_add_f32_e32 v98, v207, v98
	v_add_f32_e32 v98, v192, v98
	v_add_f32_e32 v98, v194, v98
	v_add_f32_e32 v98, v193, v98
	v_add_f32_e32 v98, v196, v98
	v_mfma_f32_32x32x16_bf16 v[64:79], v[106:109], v[138:141], v[64:79]
	v_exp_f32_e32 v108, v166
	v_add_f32_e32 v98, v195, v98
	v_exp_f32_e32 v109, v167
	v_add_f32_e32 v98, v198, v98
	v_add_f32_e32 v98, v197, v98
	v_add_f32_e32 v98, v199, v98
	v_add_f32_e32 v98, v108, v98
	v_add_f32_e32 v98, v109, v98
	v_add_f32_e32 v98, v110, v98
	v_add_f32_e32 v98, v111, v98
	v_add_f32_e32 v98, v112, v98
	v_add_f32_e32 v98, v113, v98
	v_add_f32_e32 v98, v114, v98
	v_add_f32_e32 v98, v115, v98
	v_add_f32_e32 v98, v116, v98
	v_exp_f32_e32 v121, v165
	v_add_f32_e32 v98, v117, v98
	v_add_f32_e32 v98, v118, v98
	v_add_f32_e32 v98, v119, v98
	v_add_f32_e32 v98, v120, v98
	v_add_f32_e32 v98, v121, v98
	v_add_f32_e32 v98, v122, v98
	v_add_f32_e32 v98, v123, v98
	v_mov_b32_e32 v99, v98
	v_cvt_pk_bf16_f32 v100, v200, v202
	v_cvt_pk_bf16_f32 v101, v201, v204
	v_cvt_pk_bf16_f32 v102, v203, v206
	v_cvt_pk_bf16_f32 v103, v205, v207
	s_nop 1
	v_permlane32_swap_b32_e32 v98, v99
	v_permlane32_swap_b32_e32 v100, v102
	v_permlane32_swap_b32_e32 v101, v103
	v_cvt_pk_bf16_f32 v104, v192, v194
	v_cvt_pk_bf16_f32 v105, v193, v196
	v_cvt_pk_bf16_f32 v106, v195, v198
	v_cvt_pk_bf16_f32 v107, v197, v199
	v_cvt_pk_bf16_f32 v108, v108, v109
	v_cvt_pk_bf16_f32 v109, v110, v111
	v_cvt_pk_bf16_f32 v110, v112, v113
	v_cvt_pk_bf16_f32 v111, v114, v115
	v_cvt_pk_bf16_f32 v112, v116, v117
	v_cvt_pk_bf16_f32 v113, v118, v119
	v_cvt_pk_bf16_f32 v114, v120, v121
	v_cvt_pk_bf16_f32 v115, v122, v123
	s_nop 0
	v_permlane32_swap_b32_e32 v104, v106
	v_permlane32_swap_b32_e32 v105, v107
	v_permlane32_swap_b32_e32 v108, v110
	v_permlane32_swap_b32_e32 v109, v111
	v_permlane32_swap_b32_e32 v112, v114
	v_permlane32_swap_b32_e32 v113, v115
	s_add_i32 s44, s44, 0xffff6000
	s_cmp_lg_u32 s13, 0
	s_cselect_b32 s2, s44, 0x14000
	v_add_u32_e32 v132, s2, v174
	ds_read_b64_tr_b16 v[116:117], v132 offset:0
	ds_read_b64_tr_b16 v[118:119], v132 offset:0x800
	ds_read_b64_tr_b16 v[120:121], v132 offset:0x1000
	ds_read_b64_tr_b16 v[122:123], v132 offset:0x1800
	ds_read_b64_tr_b16 v[124:125], v132 offset:0x2000
	ds_read_b64_tr_b16 v[126:127], v132 offset:0x2800
	ds_read_b64_tr_b16 v[128:129], v132 offset:0x3000
	ds_read_b64_tr_b16 v[130:131], v132 offset:0x3800
	s_waitcnt lgkmcnt(0)
; #define RESC(a) do { if (__any((a) < 1.f)) { if (hi == 0) al_l[r32] = (a); asm volatile("s_waitcnt lgkmcnt(0)" ::: "memory"); \
;     _Pragma("unroll") for (int d = 0; d < 4; ++d) _Pragma("unroll") for (int r = 0; r < 16; ++r) o[d][r] *= al_l[crow(r, hi)]; } } while (0)
; #define RESC(a) do { if (__any((a) < 1.f)) { if (hi == 0) al_l[r32] = (a); asm volatile("s_waitcnt lgkmcnt(0)" ::: "memory"); \
;     _Pragma("unroll") for (int d = 0; d < 4; ++d) _Pragma("unroll") for (int r = 0; r < 16; ++r) o[d][r] *= al_l[crow(r, hi)]; } } while (0)
; DI void partialSM(f32x16& p0, f32x16& p1, float& m_reg, float& mn, float& alpha) {
;   constexpr float C = ATT_SCALE * 1.4426950408889634f;
;   float pmax = p0[0];
; #pragma unroll
;   for (int r = 1; r < 16; ++r) pmax = fmaxf(pmax, p0[r]);
; #pragma unroll
;   for (int r = 0; r < 16; ++r) pmax = fmaxf(pmax, p1[r]);
;   { auto rr = __builtin_amdgcn_permlane32_swap(__float_as_uint(pmax), __float_as_uint(pmax), false, false);
;     pmax = fmaxf(__uint_as_float(rr[0]), __uint_as_float(rr[1])); }
;   if (__builtin_expect(__all(pmax - m_reg <= ATT_THR / ATT_SCALE), 1)) { mn = m_reg; alpha = 1.f; }
;   else { mn = fmaxf(m_reg, pmax); alpha = __builtin_amdgcn_exp2f((m_reg - mn) * C); m_reg = mn; }
; DI void attn_item_dma(const u16* Qb, const u16* Kh, const u16* Vh, const u16* Rh, u16* Ob, int seq, const float* rope, int pos0, char* lds) {
;     ...
;     pv_d0(o, vb0 + sp * STG, pa0, pa1, pa2, pa3); partialSM(pB0, pB1, m_reg, mnB, alB);
;     RESC(alB);
	s_nop 0
	v_mfma_f32_32x32x16_bf16 v[0:15], v[100:103], v[116:119], v[0:15]
	ds_read_b64_tr_b16 v[116:117], v132 offset:0x200
	ds_read_b64_tr_b16 v[118:119], v132 offset:0xa00
	v_mfma_f32_32x32x16_bf16 v[0:15], v[104:107], v[120:123], v[0:15]
	ds_read_b64_tr_b16 v[120:121], v132 offset:0x1200
	ds_read_b64_tr_b16 v[122:123], v132 offset:0x1a00
	v_mfma_f32_32x32x16_bf16 v[0:15], v[108:111], v[124:127], v[0:15]
	ds_read_b64_tr_b16 v[124:125], v132 offset:0x2200
	ds_read_b64_tr_b16 v[126:127], v132 offset:0x2a00
	v_mfma_f32_32x32x16_bf16 v[0:15], v[112:115], v[128:131], v[0:15]
	ds_read_b64_tr_b16 v[128:129], v132 offset:0x3200
	ds_read_b64_tr_b16 v[130:131], v132 offset:0x3a00
	s_waitcnt lgkmcnt(0)
	v_mfma_f32_32x32x16_bf16 v[48:63], v[100:103], v[116:119], v[48:63]
	ds_read_b64_tr_b16 v[116:117], v132 offset:0x400
	ds_read_b64_tr_b16 v[118:119], v132 offset:0xc00
	v_mfma_f32_32x32x16_bf16 v[48:63], v[104:107], v[120:123], v[48:63]
	ds_read_b64_tr_b16 v[120:121], v132 offset:0x1400
	ds_read_b64_tr_b16 v[122:123], v132 offset:0x1c00
	v_mfma_f32_32x32x16_bf16 v[48:63], v[108:111], v[124:127], v[48:63]
	ds_read_b64_tr_b16 v[124:125], v132 offset:0x2400
	ds_read_b64_tr_b16 v[126:127], v132 offset:0x2c00
	v_mfma_f32_32x32x16_bf16 v[48:63], v[112:115], v[128:131], v[48:63]
	ds_read_b64_tr_b16 v[128:129], v132 offset:0x3400
	ds_read_b64_tr_b16 v[130:131], v132 offset:0x3c00
	s_waitcnt lgkmcnt(0)
	v_mfma_f32_32x32x16_bf16 v[32:47], v[100:103], v[116:119], v[32:47]
	ds_read_b64_tr_b16 v[116:117], v132 offset:0x600
	ds_read_b64_tr_b16 v[118:119], v132 offset:0xe00
	v_mfma_f32_32x32x16_bf16 v[32:47], v[104:107], v[120:123], v[32:47]
	ds_read_b64_tr_b16 v[120:121], v132 offset:0x1600
	ds_read_b64_tr_b16 v[122:123], v132 offset:0x1e00
	v_mfma_f32_32x32x16_bf16 v[32:47], v[108:111], v[124:127], v[32:47]
	ds_read_b64_tr_b16 v[124:125], v132 offset:0x2600
	ds_read_b64_tr_b16 v[126:127], v132 offset:0x2e00
	v_mfma_f32_32x32x16_bf16 v[32:47], v[112:115], v[128:131], v[32:47]
	ds_read_b64_tr_b16 v[128:129], v132 offset:0x3600
	ds_read_b64_tr_b16 v[130:131], v132 offset:0x3e00
	s_waitcnt lgkmcnt(0)
	v_mfma_f32_32x32x16_bf16 v[16:31], v[100:103], v[116:119], v[16:31]
	v_max_f32_e32 v100, v81, v81
	v_max_f32_e32 v101, v80, v80
	v_max_f32_e32 v100, v101, v100
	v_max3_f32 v100, v100, v82, v83
	v_max3_f32 v100, v100, v84, v85
	v_max3_f32 v100, v100, v86, v87
	v_max3_f32 v100, v100, v88, v89
	v_max3_f32 v100, v100, v90, v91
	v_max3_f32 v100, v100, v92, v93
	v_mfma_f32_32x32x16_bf16 v[16:31], v[104:107], v[120:123], v[16:31]
	v_max3_f32 v100, v100, v94, v95
	v_max3_f32 v100, v100, v64, v65
	v_max3_f32 v100, v100, v66, v67
	v_max3_f32 v100, v100, v68, v69
	v_max3_f32 v100, v100, v70, v71
	v_max3_f32 v100, v100, v72, v73
	v_max3_f32 v100, v100, v74, v75
	v_max3_f32 v100, v100, v76, v77
	v_mfma_f32_32x32x16_bf16 v[16:31], v[108:111], v[124:127], v[16:31]
	v_max3_f32 v100, v100, v78, v79
	v_mov_b32_e32 v101, v100
	s_nop 1
	v_permlane32_swap_b32_e32 v100, v101
	v_max_f32_e32 v101, v101, v101
	v_max_f32_e32 v100, v100, v100
	v_max_f32_e32 v100, v100, v101
	v_sub_f32_e32 v101, v100, v187
	v_cmp_ge_f32_e32 vcc, s65, v101
	v_max_f32_e32 v101, v187, v187
	v_max_f32_e32 v101, v101, v100
	v_mfma_f32_32x32x16_bf16 v[16:31], v[112:115], v[128:131], v[16:31]
	v_sub_f32_e32 v100, v187, v101
	v_mul_f32_e32 v100, 0x3dd53b94, v100
	v_exp_f32_e32 v100, v100
	s_cmp_eq_u64 vcc, exec
	s_cselect_b64 s[38:39], -1, 0
	v_cndmask_b32_e64 v100, v100, 1.0, s[38:39]
	v_cmp_gt_f32_e32 vcc, 1.0, v100
	s_cbranch_vccz .LBB0_140
	s_and_saveexec_b64 s[6:7], s[36:37]
	ds_write_b32 v172, v100 offset:128
	s_or_b64 exec, exec, s[6:7]
	s_waitcnt lgkmcnt(0)
	v_add_u32_e32 v114, v147, v96
	ds_read_b128 v[102:105], v114 offset:224
	ds_read_b128 v[106:109], v114 offset:192
	ds_read_b128 v[110:113], v114 offset:160
	ds_read_b128 v[114:117], v114 offset:128
	s_waitcnt lgkmcnt(0)
	v_pk_mul_f32 v[12:13], v[12:13], v[102:103]
	v_pk_mul_f32 v[8:9], v[8:9], v[106:107]
	v_pk_mul_f32 v[4:5], v[4:5], v[110:111]
	v_pk_mul_f32 v[14:15], v[14:15], v[104:105]
	v_pk_mul_f32 v[10:11], v[10:11], v[108:109]
	v_pk_mul_f32 v[6:7], v[6:7], v[112:113]
	v_pk_mul_f32 v[2:3], v[2:3], v[116:117]
	v_pk_mul_f32 v[0:1], v[0:1], v[114:115]
	v_pk_mul_f32 v[60:61], v[60:61], v[102:103]
	v_pk_mul_f32 v[56:57], v[56:57], v[106:107]
	v_pk_mul_f32 v[52:53], v[52:53], v[110:111]
	v_pk_mul_f32 v[62:63], v[62:63], v[104:105]
	v_pk_mul_f32 v[58:59], v[58:59], v[108:109]
	v_pk_mul_f32 v[54:55], v[54:55], v[112:113]
	v_pk_mul_f32 v[50:51], v[50:51], v[116:117]
	v_pk_mul_f32 v[48:49], v[48:49], v[114:115]
	v_pk_mul_f32 v[44:45], v[44:45], v[102:103]
	v_pk_mul_f32 v[40:41], v[40:41], v[106:107]
	v_pk_mul_f32 v[36:37], v[36:37], v[110:111]
	v_pk_mul_f32 v[46:47], v[46:47], v[104:105]
	v_pk_mul_f32 v[42:43], v[42:43], v[108:109]
	v_pk_mul_f32 v[38:39], v[38:39], v[112:113]
	v_pk_mul_f32 v[34:35], v[34:35], v[116:117]
	v_pk_mul_f32 v[32:33], v[32:33], v[114:115]
	v_pk_mul_f32 v[28:29], v[28:29], v[102:103]
	v_pk_mul_f32 v[24:25], v[24:25], v[106:107]
	v_pk_mul_f32 v[20:21], v[20:21], v[110:111]
	v_pk_mul_f32 v[30:31], v[30:31], v[104:105]
	v_pk_mul_f32 v[26:27], v[26:27], v[108:109]
	v_pk_mul_f32 v[22:23], v[22:23], v[112:113]
	v_pk_mul_f32 v[18:19], v[18:19], v[116:117]
	v_pk_mul_f32 v[16:17], v[16:17], v[114:115]
